# select pass-0 scan: reduction split over two accumulators (shorter dependent add chain)
# speedup vs baseline: 1.0007x; 1.0007x over previous
; template <int PASS>
; DI void sel_pass(SelSmem* S, const uint32_t (&sk)[32][2], int ntiles, uint32_t (&pf)[2]) {
;     ...
;   {
;     constexpr int PER = (PASS == 0 || PASS == 3) ? 64 : 16;
;     const int pair = wave >> 1, sh = (wave & 1) * 16;
;     const uint32_t need = S->need[wave];
;     const uint32_t prevp = S->pfx[wave];
;     const uint32_t* hp = &S->hist[pair][lane * PER];
;     uint32_t tot = 0;
;     for (int c = 0; c < PER; ++c) tot += (hp[(c + lane) & (PER - 1)] >> sh) & 0xffffu;
;     uint32_t incl = tot;
; #pragma unroll
;     for (int off = 1; off < 64; off <<= 1) {
;       uint32_t v = __shfl_down(incl, off);
;       if (lane + off < 64) incl += v;
;     }
;     const uint32_t sfx = incl - tot;
;     const bool cross = (sfx < need) && (need <= sfx + tot);
.LBB0_587:
	s_lshl_b32 s0, s44, 7
	v_and_b32_e32 v5, 63, v1
	s_and_b32 s18, s0, 0xffffc000
	v_add_u32_e32 v9, 1, v1
	s_lshl_b32 s16, s15, 4
	s_lshl_b32 s15, s15, 2
	v_lshl_or_b32 v7, v5, 8, s18
	v_and_b32_e32 v9, 63, v9
	v_mov_b32_e32 v4, s15
	v_lshl_or_b32 v8, v5, 2, v7
	v_lshl_or_b32 v9, v9, 2, v7
	s_waitcnt lgkmcnt(0)
	s_barrier
	ds_read_b32 v4, v4 offset:32784
	v_and_b32_e32 v9, 15, v5
	v_mov_b32_e32 v8, 0
	v_mov_b32_e32 v15, 0
	v_lshl_or_b32 v10, v9, 4, v7
	ds_read_b128 v[96:99], v10
	v_add_u32_e32 v10, 1, v9
	v_and_b32_e32 v10, 15, v10
	v_lshl_or_b32 v10, v10, 4, v7
	ds_read_b128 v[100:103], v10
	v_add_u32_e32 v10, 2, v9
	v_and_b32_e32 v10, 15, v10
	v_lshl_or_b32 v10, v10, 4, v7
	ds_read_b128 v[104:107], v10
	v_add_u32_e32 v10, 3, v9
	v_and_b32_e32 v10, 15, v10
	v_lshl_or_b32 v10, v10, 4, v7
	ds_read_b128 v[130:133], v10
	v_add_u32_e32 v10, 4, v9
	v_and_b32_e32 v10, 15, v10
	v_lshl_or_b32 v10, v10, 4, v7
	ds_read_b128 v[190:193], v10
	v_add_u32_e32 v10, 5, v9
	v_and_b32_e32 v10, 15, v10
	v_lshl_or_b32 v10, v10, 4, v7
	ds_read_b128 v[194:197], v10
	v_add_u32_e32 v10, 6, v9
	v_and_b32_e32 v10, 15, v10
	v_lshl_or_b32 v10, v10, 4, v7
	ds_read_b128 v[198:201], v10
	v_add_u32_e32 v10, 7, v9
	v_and_b32_e32 v10, 15, v10
	v_lshl_or_b32 v10, v10, 4, v7
	ds_read_b128 v[230:233], v10
	v_and_b32_e32 v11, 63, v213
	v_cmp_ne_u32_e32 vcc, 63, v11
	v_cmp_eq_u32_e64 s[0:1], 63, v5
	v_cmp_gt_u32_e64 s[44:45], 62, v5
	v_cmp_gt_u32_e64 s[46:47], 60, v5
	v_cmp_gt_u32_e64 s[48:49], 56, v5
	v_cmp_gt_u32_e64 s[50:51], 48, v5
	v_cmp_gt_u32_e64 s[52:53], 32, v5
	s_mov_b32 s55, s57
	s_waitcnt lgkmcnt(0)
	v_bfe_u32 v96, v96, s16, 16
	v_bfe_u32 v97, v97, s16, 16
	v_bfe_u32 v98, v98, s16, 16
	v_bfe_u32 v99, v99, s16, 16
	v_add3_u32 v8, v8, v96, v97
	v_add3_u32 v15, v15, v98, v99
	v_bfe_u32 v100, v100, s16, 16
	v_bfe_u32 v101, v101, s16, 16
	v_bfe_u32 v102, v102, s16, 16
	v_bfe_u32 v103, v103, s16, 16
	v_add3_u32 v8, v8, v100, v101
	v_add3_u32 v15, v15, v102, v103
	v_bfe_u32 v104, v104, s16, 16
	v_bfe_u32 v105, v105, s16, 16
	v_bfe_u32 v106, v106, s16, 16
	v_bfe_u32 v107, v107, s16, 16
	v_add3_u32 v8, v8, v104, v105
	v_add3_u32 v15, v15, v106, v107
	v_bfe_u32 v130, v130, s16, 16
	v_bfe_u32 v131, v131, s16, 16
	v_bfe_u32 v132, v132, s16, 16
	v_bfe_u32 v133, v133, s16, 16
	v_add3_u32 v8, v8, v130, v131
	v_add3_u32 v15, v15, v132, v133
	v_bfe_u32 v190, v190, s16, 16
	v_bfe_u32 v191, v191, s16, 16
	v_bfe_u32 v192, v192, s16, 16
	v_bfe_u32 v193, v193, s16, 16
	v_add3_u32 v8, v8, v190, v191
	v_add3_u32 v15, v15, v192, v193
	v_bfe_u32 v194, v194, s16, 16
	v_bfe_u32 v195, v195, s16, 16
	v_bfe_u32 v196, v196, s16, 16
	v_bfe_u32 v197, v197, s16, 16
	v_add3_u32 v8, v8, v194, v195
	v_add3_u32 v15, v15, v196, v197
	v_bfe_u32 v198, v198, s16, 16
	v_bfe_u32 v199, v199, s16, 16
	v_bfe_u32 v200, v200, s16, 16
	v_bfe_u32 v201, v201, s16, 16
	v_add3_u32 v8, v8, v198, v199
	v_add3_u32 v15, v15, v200, v201
	v_bfe_u32 v230, v230, s16, 16
	v_bfe_u32 v231, v231, s16, 16
	v_bfe_u32 v232, v232, s16, 16
	v_bfe_u32 v233, v233, s16, 16
	v_add3_u32 v8, v8, v230, v231
	v_add3_u32 v15, v15, v232, v233
	v_add_u32_e32 v10, 8, v9
	v_and_b32_e32 v10, 15, v10
	v_lshl_or_b32 v10, v10, 4, v7
	ds_read_b128 v[96:99], v10
	v_add_u32_e32 v10, 9, v9
	v_and_b32_e32 v10, 15, v10
	v_lshl_or_b32 v10, v10, 4, v7
	ds_read_b128 v[100:103], v10
	v_add_u32_e32 v10, 10, v9
	v_and_b32_e32 v10, 15, v10
	v_lshl_or_b32 v10, v10, 4, v7
	ds_read_b128 v[104:107], v10
	v_add_u32_e32 v10, 11, v9
	v_and_b32_e32 v10, 15, v10
	v_lshl_or_b32 v10, v10, 4, v7
	ds_read_b128 v[130:133], v10
	v_add_u32_e32 v10, 12, v9
	v_and_b32_e32 v10, 15, v10
	v_lshl_or_b32 v10, v10, 4, v7
	ds_read_b128 v[190:193], v10
	v_add_u32_e32 v10, 13, v9
	v_and_b32_e32 v10, 15, v10
	v_lshl_or_b32 v10, v10, 4, v7
	ds_read_b128 v[194:197], v10
	v_add_u32_e32 v10, 14, v9
	v_and_b32_e32 v10, 15, v10
	v_lshl_or_b32 v10, v10, 4, v7
	ds_read_b128 v[198:201], v10
	v_add_u32_e32 v10, 15, v9
	v_and_b32_e32 v10, 15, v10
	v_lshl_or_b32 v10, v10, 4, v7
	ds_read_b128 v[230:233], v10
	s_waitcnt lgkmcnt(0)
	v_bfe_u32 v96, v96, s16, 16
	v_bfe_u32 v97, v97, s16, 16
	v_bfe_u32 v98, v98, s16, 16
	v_bfe_u32 v99, v99, s16, 16
	v_add3_u32 v8, v8, v96, v97
	v_add3_u32 v15, v15, v98, v99
	v_bfe_u32 v100, v100, s16, 16
	v_bfe_u32 v101, v101, s16, 16
	v_bfe_u32 v102, v102, s16, 16
	v_bfe_u32 v103, v103, s16, 16
	v_add3_u32 v8, v8, v100, v101
	v_add3_u32 v15, v15, v102, v103
	v_bfe_u32 v104, v104, s16, 16
	v_bfe_u32 v105, v105, s16, 16
	v_bfe_u32 v106, v106, s16, 16
	v_bfe_u32 v107, v107, s16, 16
	v_add3_u32 v8, v8, v104, v105
	v_add3_u32 v15, v15, v106, v107
	v_bfe_u32 v130, v130, s16, 16
	v_bfe_u32 v131, v131, s16, 16
	v_bfe_u32 v132, v132, s16, 16
	v_bfe_u32 v133, v133, s16, 16
	v_add3_u32 v8, v8, v130, v131
	v_add3_u32 v15, v15, v132, v133
	v_bfe_u32 v190, v190, s16, 16
	v_bfe_u32 v191, v191, s16, 16
	v_bfe_u32 v192, v192, s16, 16
	v_bfe_u32 v193, v193, s16, 16
	v_add3_u32 v8, v8, v190, v191
	v_add3_u32 v15, v15, v192, v193
	v_bfe_u32 v194, v194, s16, 16
	v_bfe_u32 v195, v195, s16, 16
	v_bfe_u32 v196, v196, s16, 16
	v_bfe_u32 v197, v197, s16, 16
	v_add3_u32 v8, v8, v194, v195
	v_add3_u32 v15, v15, v196, v197
	v_bfe_u32 v198, v198, s16, 16
	v_bfe_u32 v199, v199, s16, 16
	v_bfe_u32 v200, v200, s16, 16
	v_bfe_u32 v201, v201, s16, 16
	v_add3_u32 v8, v8, v198, v199
	v_add3_u32 v15, v15, v200, v201
	v_bfe_u32 v230, v230, s16, 16
	v_bfe_u32 v231, v231, s16, 16
	v_bfe_u32 v232, v232, s16, 16
	v_bfe_u32 v233, v233, s16, 16
	v_add3_u32 v8, v8, v230, v231
	v_add3_u32 v15, v15, v232, v233
	v_add_u32_e32 v8, v8, v15
	v_addc_co_u32_e32 v7, vcc, 0, v213, vcc
	v_lshlrev_b32_e32 v7, 2, v7
	v_mov_b32_e32 v1, v8
	ds_bpermute_b32 v8, v7, v1
	v_cmp_gt_u32_e32 vcc, 62, v11
	s_waitcnt lgkmcnt(0)
	v_cndmask_b32_e64 v8, v8, 0, s[0:1]
	v_add_u32_e32 v9, v8, v1
	v_cndmask_b32_e64 v8, 0, 2, vcc
	v_add_lshl_u32 v8, v8, v213, 2
	ds_bpermute_b32 v10, v8, v9
	v_cmp_gt_u32_e32 vcc, 60, v11
	s_waitcnt lgkmcnt(0)
	v_cndmask_b32_e64 v10, 0, v10, s[44:45]
	v_add_u32_e32 v10, v10, v9
	v_cndmask_b32_e64 v9, 0, 4, vcc
	v_add_lshl_u32 v9, v9, v213, 2
	ds_bpermute_b32 v12, v9, v10
	v_cmp_gt_u32_e32 vcc, 56, v11
	s_waitcnt lgkmcnt(0)
	v_cndmask_b32_e64 v12, 0, v12, s[46:47]
	v_add_u32_e32 v12, v12, v10
	v_cndmask_b32_e64 v10, 0, 8, vcc
	v_add_lshl_u32 v10, v10, v213, 2
	ds_bpermute_b32 v13, v10, v12
	v_cmp_gt_u32_e32 vcc, 48, v11
	s_waitcnt lgkmcnt(0)
	v_cndmask_b32_e64 v13, 0, v13, s[48:49]
	v_cndmask_b32_e64 v11, 0, 16, vcc
	v_add_u32_e32 v12, v13, v12
	v_add_lshl_u32 v11, v11, v213, 2
	ds_bpermute_b32 v13, v11, v12
	s_waitcnt lgkmcnt(0)
	v_cndmask_b32_e64 v13, 0, v13, s[50:51]
	v_add_u32_e32 v13, v13, v12
	v_lshl_or_b32 v12, v213, 2, v227
	ds_bpermute_b32 v14, v12, v13
	s_waitcnt lgkmcnt(0)
	v_cndmask_b32_e64 v14, 0, v14, s[52:53]
	v_add_u32_e32 v14, v14, v13
	v_sub_u32_e32 v13, v14, v1
	v_cmp_lt_u32_e32 vcc, v13, v4
	v_cmp_le_u32_e64 s[56:57], v4, v14
	s_and_b64 vcc, s[56:57], vcc
	v_cndmask_b32_e64 v1, 0, 1, vcc
	v_cmp_ne_u32_e64 s[56:57], 0, v1
	s_cbranch_vccz .LBB0_591
; template <int PASS>
; DI void sel_pass(SelSmem* S, const uint32_t (&sk)[32][2], int ntiles, uint32_t (&pf)[2]) {
;     ...
;     if (cm != 0ull) {
;       const int L = __builtin_ctzll(cm);
;       const uint32_t cumbase = (uint32_t)__shfl((int)sfx, L);
;       const uint32_t cnt = (lane < PER) ? ((S->hist[pair][L * PER + lane] >> sh) & 0xffffu) : 0u;
;       uint32_t inc2 = cnt;
; #pragma unroll
;       for (int off = 1; off < PER; off <<= 1) {
;         uint32_t v = __shfl_down(inc2, off);
;         if (lane + off < 64) inc2 += v;
;       }
;       const uint32_t cum = cumbase + (inc2 - cnt);
;       if (lane < PER && cum < need && need <= cum + cnt) {
;         const uint32_t bin = (uint32_t)(L * PER + lane);
;         const uint32_t nn = need - cum;
;         if (PASS == 0) S->pfx[wave] = bin;
;         else if (PASS == 1 || PASS == 2) S->pfx[wave] = (prevp << 10) | bin;
;         else S->dcut[wave] = bin;
;         if (PASS == 2 && cnt != nn) atomicOr(&S->flag, 1u);
;         if (PASS == 1 && cnt != nn) atomicOr(&S->flag, 2u);
;         S->need[wave] = nn;
;       }
	s_ff1_i32_b64 s19, s[56:57]
	v_lshl_or_b32 v1, s19, 6, v5
	v_lshl_add_u32 v5, v1, 2, s18
	ds_read_b32 v5, v5
	s_and_b32 s16, s16, 16
	v_and_or_b32 v16, v213, 64, s19
	v_lshlrev_b32_e32 v16, 2, v16
	ds_bpermute_b32 v13, v16, v13
	s_waitcnt lgkmcnt(1)
	v_lshrrev_b32_e32 v5, s16, v5
	v_and_b32_e32 v5, 0xffff, v5
	ds_bpermute_b32 v14, v7, v5
	s_waitcnt lgkmcnt(0)
	v_cndmask_b32_e64 v14, v14, 0, s[0:1]
	v_add_u32_e32 v14, v5, v14
	ds_bpermute_b32 v15, v8, v14
	s_waitcnt lgkmcnt(0)
	v_cndmask_b32_e64 v15, 0, v15, s[44:45]
	v_add_u32_e32 v14, v14, v15
	ds_bpermute_b32 v15, v9, v14
	s_waitcnt lgkmcnt(0)
	v_cndmask_b32_e64 v15, 0, v15, s[46:47]
	v_add_u32_e32 v14, v14, v15
	ds_bpermute_b32 v15, v10, v14
	s_waitcnt lgkmcnt(0)
	v_cndmask_b32_e64 v15, 0, v15, s[48:49]
	v_add_u32_e32 v14, v14, v15
	ds_bpermute_b32 v15, v11, v14
	s_waitcnt lgkmcnt(0)
	v_cndmask_b32_e64 v15, 0, v15, s[50:51]
	v_add_u32_e32 v14, v14, v15
	ds_bpermute_b32 v15, v12, v14
	s_waitcnt lgkmcnt(0)
	v_cndmask_b32_e64 v15, 0, v15, s[52:53]
	v_add_u32_e32 v14, v14, v15
	v_sub_u32_e32 v5, v14, v5
	v_add_u32_e32 v14, v14, v13
	v_add_u32_e32 v5, v5, v13
	v_cmp_gt_u32_e32 vcc, v4, v5
	v_cmp_le_u32_e64 s[0:1], v4, v14
	s_and_b64 s[18:19], s[0:1], vcc
	s_and_saveexec_b64 s[0:1], s[18:19]
	v_sub_u32_e32 v4, v4, v5
	v_mov_b32_e32 v5, s15
	v_add_u32_e32 v5, 0x8000, v5
	ds_write2_b32 v5, v1, v4 offset1:4
	s_or_b64 exec, exec, s[0:1]
